# EpiConv: exp/rcp interleaved with independent packed-f32 work (value-half conv, next block's row scaling) to overlap the transcendental pipe with the main VALU
# speedup vs baseline: 1.0073x; 1.0073x over previous
;     __device__ __forceinline__ void operator()(const f32x4 (&acc)[2][2][4][2], const Unit& u, int wr, int wc, int fr, int fq) const {
;     ...
;             for (int m = 0; m < 4; ++m) { const int t = tbase + 16 * m + fr; const bool vin = (t >= 0) && (t < slen); const int grow = seqbase + (vin ? t : 0);
;                 const f32x4 p = *(const f32x4*)(PS + (size_t)grow * 16 + 4 * fq); float s = (p[0] + p[1]) + (p[2] + p[3]); s = bfly_add<16>(s); s = bfly_add<32>(s); rs[m] = vin ? rsqrtf(s * (1.f / DM) + EPS) : 0.f; }
;             unsigned outw[4][2][2];
; #pragma unroll
;             for (int n = 0; n < 2; ++n)
; #pragma unroll
;                 for (int jp = 0; jp < 2; ++jp) {
;                     const int cidx = (4 * n + 2 * jp) * 2;
;                     const f32x4 c0a = ct[cidx], c0b = ct[cidx + 1], c1a = ct[cidx + 2], c1b = ct[cidx + 3];
;                     const f32x2 wv0 = {c0a[0], c1a[0]}, wv1 = {c0a[1], c1a[1]}, wv2 = {c0a[2], c1a[2]}, bv = {c0a[3], c1a[3]};
;                     const f32x2 wg0 = {c0b[0], c1b[0]}, wg1 = {c0b[1], c1b[1]}, wg2 = {c0b[2], c1b[2]}, bg = {c0b[3], c1b[3]};
;                     f32x2 uv[4], ug[4], cv[4];
; #pragma unroll
;                     for (int m = 0; m < 4; ++m) { uv[m] = (f32x2){acc[ai][0][m][n][2 * jp], acc[ai][0][m][n][2 * jp + 1]}; ug[m] = (f32x2){acc[ai][1][m][n][2 * jp], acc[ai][1][m][n][2 * jp + 1]}; }
;                     asm volatile("" : "+v"(uv[0]), "+v"(uv[1]), "+v"(uv[2]), "+v"(uv[3]), "+v"(ug[0]), "+v"(ug[1]), "+v"(ug[2]), "+v"(ug[3]));
;                     {
;                         f32x2 rv[4], lv[4];
; #pragma unroll
;                         for (int m = 0; m < 4; ++m) { uv[m] = uv[m] * rs[m]; rv[m] = (f32x2){dpp_ror1(uv[m][0]), dpp_ror1(uv[m][1])}; lv[m] = (f32x2){dpp_ror15(uv[m][0]), dpp_ror15(uv[m][1])}; }
; #pragma unroll
;                         for (int m = 0; m < 4; ++m) { const f32x2 pv_ = (m > 0 && f0) ? rv[m > 0 ? m - 1 : 0] : rv[m], nv_ = (m < 3 && f15) ? lv[m < 3 ? m + 1 : 3] : lv[m];
;                             cv[m] = bv + wv0 * pv_ + wv1 * uv[m] + wv2 * nv_; }
;                     }
;                     asm volatile("" : "+v"(cv[0]), "+v"(cv[1]), "+v"(cv[2]), "+v"(cv[3]));
;                     {
;                         f32x2 rg[4], lg[4];
; #pragma unroll
.LBB0_790:
	s_lshl_b32 s92, s33, 12
	s_add_u32 s64, s100, s92
	s_addc_u32 s65, s101, 0
	s_lshl_b32 s92, s33, 8
	s_add_u32 s86, s98, s92
	s_addc_u32 s87, s99, 0
	v_mov_b32_e32 v252, s78
	s_movk_i32 s54, 0x1600
	global_load_dwordx4 v[190:193], v172, s[64:65]
	global_load_dwordx4 v[194:197], v172, s[64:65] offset:16
	global_load_dwordx4 v[198:201], v172, s[64:65] offset:32
	global_load_dwordx4 v[202:205], v172, s[64:65] offset:48
	v_lshrrev_b32_e32 v176, 4, v165
	v_add_u32_e32 v176, v176, v174
	v_cmp_gt_u32_e32 vcc, s91, v176
	s_waitcnt vmcnt(4)
	v_pk_add_f32 v[240:241], v[240:241], v[244:245]
	v_pk_add_f32 v[242:243], v[242:243], v[246:247]
	v_pk_add_f32 v[248:249], v[248:249], v[160:161]
	v_pk_add_f32 v[250:251], v[250:251], v[162:163]
	v_pk_add_f32 v[240:241], v[240:241], v[248:249]
	v_pk_add_f32 v[242:243], v[242:243], v[250:251]
	v_pk_add_f32 v[240:241], v[240:241], v[242:243]
	v_add_f32_e32 v240, v240, v241
	v_fma_f32 v240, v240, s82, v252
	v_rsq_f32_e32 v240, v240
	s_nop 0
	v_cndmask_b32_e32 v178, 0, v240, vcc
	v_mov_b32_e32 v180, v178
	s_nop 1
	v_permlane16_swap_b32_e32 v178, v180
	v_mov_b32_e32 v182, v178
	v_mov_b32_e32 v144, v180
	s_nop 1
	v_permlane32_swap_b32_e32 v178, v182
	v_permlane32_swap_b32_e32 v180, v144
	v_pk_mul_f32 v[124:125], v[124:125], v[178:179] op_sel_hi:[1,0]
	v_pk_mul_f32 v[120:121], v[120:121], v[180:181] op_sel_hi:[1,0]
	v_pk_mul_f32 v[116:117], v[116:117], v[182:183] op_sel_hi:[1,0]
	v_pk_mul_f32 v[112:113], v[112:113], v[144:145] op_sel_hi:[1,0]
	v_pk_mul_f32 v[108:109], v[108:109], v[178:179] op_sel_hi:[1,0]
	v_pk_mul_f32 v[104:105], v[104:105], v[180:181] op_sel_hi:[1,0]
	v_pk_mul_f32 v[100:101], v[100:101], v[182:183] op_sel_hi:[1,0]
	v_pk_mul_f32 v[96:97], v[96:97], v[144:145] op_sel_hi:[1,0]
	global_load_dwordx4 v[206:209], v172, s[64:65] offset:64
	global_load_dwordx4 v[210:213], v172, s[64:65] offset:80
	global_load_dwordx4 v[214:217], v172, s[64:65] offset:96
	global_load_dwordx4 v[218:221], v172, s[64:65] offset:112
	s_waitcnt vmcnt(4)
	v_pk_fma_f32 v[232:233], v[200:201], v[108:109], v[204:205]
	v_pk_fma_f32 v[234:235], v[198:199], v[108:109], v[204:205]
	v_pk_fma_f32 v[236:237], v[198:199], v[104:105], v[204:205]
	v_pk_fma_f32 v[238:239], v[198:199], v[100:101], v[204:205]
	v_pk_fma_f32 v[232:233], v[202:203], v[104:105], v[232:233]
	v_pk_fma_f32 v[234:235], v[200:201], v[104:105], v[234:235]
	v_pk_fma_f32 v[236:237], v[200:201], v[100:101], v[236:237]
	v_pk_fma_f32 v[238:239], v[200:201], v[96:97], v[238:239]
	v_pk_fma_f32 v[234:235], v[202:203], v[100:101], v[234:235]
	v_pk_fma_f32 v[236:237], v[202:203], v[96:97], v[236:237]
	v_fmac_f32_dpp v232, v96, v198 row_shr:1 row_mask:0xf bank_mask:0xf bound_ctrl:1
	v_fmac_f32_dpp v233, v97, v199 row_shr:1 row_mask:0xf bank_mask:0xf bound_ctrl:1
	v_fmac_f32_dpp v238, v108, v202 row_shl:1 row_mask:0xf bank_mask:0xf bound_ctrl:1
	v_fmac_f32_dpp v239, v109, v203 row_shl:1 row_mask:0xf bank_mask:0xf bound_ctrl:1
	v_exp_f32_e64 v240, -v232
	v_pk_fma_f32 v[224:225], v[192:193], v[124:125], v[196:197]
	v_pk_fma_f32 v[226:227], v[190:191], v[124:125], v[196:197]
	v_exp_f32_e64 v241, -v233
	v_pk_fma_f32 v[228:229], v[190:191], v[120:121], v[196:197]
	v_pk_fma_f32 v[230:231], v[190:191], v[116:117], v[196:197]
	v_exp_f32_e64 v242, -v234
	v_pk_fma_f32 v[224:225], v[194:195], v[120:121], v[224:225]
	v_pk_fma_f32 v[226:227], v[192:193], v[120:121], v[226:227]
	v_exp_f32_e64 v243, -v235
	v_pk_fma_f32 v[228:229], v[192:193], v[116:117], v[228:229]
	v_pk_fma_f32 v[230:231], v[192:193], v[112:113], v[230:231]
	v_exp_f32_e64 v244, -v236
	v_pk_fma_f32 v[226:227], v[194:195], v[116:117], v[226:227]
	v_pk_fma_f32 v[228:229], v[194:195], v[112:113], v[228:229]
	v_exp_f32_e64 v245, -v237
	v_fmac_f32_dpp v224, v112, v190 row_shr:1 row_mask:0xf bank_mask:0xf bound_ctrl:1
	v_fmac_f32_dpp v225, v113, v191 row_shr:1 row_mask:0xf bank_mask:0xf bound_ctrl:1
	v_exp_f32_e64 v246, -v238
	v_fmac_f32_dpp v230, v124, v194 row_shl:1 row_mask:0xf bank_mask:0xf bound_ctrl:1
	v_fmac_f32_dpp v231, v125, v195 row_shl:1 row_mask:0xf bank_mask:0xf bound_ctrl:1
	v_exp_f32_e64 v247, -v239
	v_pk_add_f32 v[240:241], v[240:241], 1.0 op_sel_hi:[1,0]
	v_pk_add_f32 v[242:243], v[242:243], 1.0 op_sel_hi:[1,0]
	v_pk_add_f32 v[244:245], v[244:245], 1.0 op_sel_hi:[1,0]
	v_pk_add_f32 v[246:247], v[246:247], 1.0 op_sel_hi:[1,0]
	v_rcp_f32_e32 v240, v240
	v_pk_mul_f32 v[224:225], v[224:225], v[232:233]
	v_pk_mul_f32 v[226:227], v[226:227], v[234:235]
	v_rcp_f32_e32 v241, v241
	v_pk_mul_f32 v[228:229], v[228:229], v[236:237]
	v_pk_mul_f32 v[230:231], v[230:231], v[238:239]
	v_rcp_f32_e32 v242, v242
	v_pk_mul_f32 v[126:127], v[126:127], v[178:179] op_sel_hi:[1,0]
	v_pk_mul_f32 v[122:123], v[122:123], v[180:181] op_sel_hi:[1,0]
	v_rcp_f32_e32 v243, v243
	v_pk_mul_f32 v[118:119], v[118:119], v[182:183] op_sel_hi:[1,0]
	v_pk_mul_f32 v[114:115], v[114:115], v[144:145] op_sel_hi:[1,0]
	v_rcp_f32_e32 v244, v244
	v_pk_mul_f32 v[110:111], v[110:111], v[178:179] op_sel_hi:[1,0]
	v_pk_mul_f32 v[106:107], v[106:107], v[180:181] op_sel_hi:[1,0]
	v_rcp_f32_e32 v245, v245
	v_pk_mul_f32 v[102:103], v[102:103], v[182:183] op_sel_hi:[1,0]
	v_rcp_f32_e32 v246, v246
	v_pk_mul_f32 v[98:99], v[98:99], v[144:145] op_sel_hi:[1,0]
	v_rcp_f32_e32 v247, v247
	s_nop 0
	v_pk_mul_f32 v[224:225], v[224:225], v[240:241]
	v_pk_mul_f32 v[226:227], v[226:227], v[242:243]
	v_pk_mul_f32 v[228:229], v[228:229], v[244:245]
	v_pk_mul_f32 v[230:231], v[230:231], v[246:247]
	v_cvt_pk_bf16_f32 v128, v224, v225
	v_cvt_pk_bf16_f32 v132, v226, v227
	v_cvt_pk_bf16_f32 v136, v228, v229
	v_cvt_pk_bf16_f32 v140, v230, v231
	global_load_dwordx4 v[190:193], v172, s[64:65] offset:128
	global_load_dwordx4 v[194:197], v172, s[64:65] offset:144
	global_load_dwordx4 v[198:201], v172, s[64:65] offset:160
	global_load_dwordx4 v[202:205], v172, s[64:65] offset:176
	s_waitcnt vmcnt(4)
;     __device__ __forceinline__ void operator()(const f32x4 (&acc)[2][2][4][2], const Unit& u, int wr, int wc, int fr, int fq) const {
;     ...
;                     const f32x4 c0a = ct[cidx], c0b = ct[cidx + 1], c1a = ct[cidx + 2], c1b = ct[cidx + 3];
;                     const f32x2 wv0 = {c0a[0], c1a[0]}, wv1 = {c0a[1], c1a[1]}, wv2 = {c0a[2], c1a[2]}, bv = {c0a[3], c1a[3]};
;                     const f32x2 wg0 = {c0b[0], c1b[0]}, wg1 = {c0b[1], c1b[1]}, wg2 = {c0b[2], c1b[2]}, bg = {c0b[3], c1b[3]};
;                     f32x2 uv[4], ug[4], cv[4];
; #pragma unroll
;                     for (int m = 0; m < 4; ++m) { uv[m] = (f32x2){acc[ai][0][m][n][2 * jp], acc[ai][0][m][n][2 * jp + 1]}; ug[m] = (f32x2){acc[ai][1][m][n][2 * jp], acc[ai][1][m][n][2 * jp + 1]}; }
;                     asm volatile("" : "+v"(uv[0]), "+v"(uv[1]), "+v"(uv[2]), "+v"(uv[3]), "+v"(ug[0]), "+v"(ug[1]), "+v"(ug[2]), "+v"(ug[3]));
;                     {
;                         f32x2 rv[4], lv[4];
; #pragma unroll
;                         for (int m = 0; m < 4; ++m) { uv[m] = uv[m] * rs[m]; rv[m] = (f32x2){dpp_ror1(uv[m][0]), dpp_ror1(uv[m][1])}; lv[m] = (f32x2){dpp_ror15(uv[m][0]), dpp_ror15(uv[m][1])}; }
; #pragma unroll
;                         for (int m = 0; m < 4; ++m) { const f32x2 pv_ = (m > 0 && f0) ? rv[m > 0 ? m - 1 : 0] : rv[m], nv_ = (m < 3 && f15) ? lv[m < 3 ? m + 1 : 3] : lv[m];
;                             cv[m] = bv + wv0 * pv_ + wv1 * uv[m] + wv2 * nv_; }
;                     }
;                     asm volatile("" : "+v"(cv[0]), "+v"(cv[1]), "+v"(cv[2]), "+v"(cv[3]));
;                     {
;                         f32x2 rg[4], lg[4];
; #pragma unroll
;                         for (int m = 0; m < 4; ++m) { ug[m] = ug[m] * rs[m]; rg[m] = (f32x2){dpp_ror1(ug[m][0]), dpp_ror1(ug[m][1])}; lg[m] = (f32x2){dpp_ror15(ug[m][0]), dpp_ror15(ug[m][1])}; }
; #pragma unroll
;                         for (int m = 0; m < 4; ++m) { const f32x2 pg_ = (m > 0 && f0) ? rg[m > 0 ? m - 1 : 0] : rg[m], ng_ = (m < 3 && f15) ? lg[m < 3 ? m + 1 : 3] : lg[m];
;                             const f32x2 cgt = bg + wg0 * pg_ + wg1 * ug[m] + wg2 * ng_;
;                             const f32x2 e = cgt * (-LOG2E);
;                             const f32x2 d = (f32x2){__builtin_amdgcn_exp2f(e[0]), __builtin_amdgcn_exp2f(e[1])} + 1.f;
	v_pk_fma_f32 v[232:233], v[216:217], v[110:111], v[220:221]
	v_pk_fma_f32 v[234:235], v[214:215], v[110:111], v[220:221]
	v_pk_fma_f32 v[236:237], v[214:215], v[106:107], v[220:221]
	v_pk_fma_f32 v[238:239], v[214:215], v[102:103], v[220:221]
	v_pk_fma_f32 v[232:233], v[218:219], v[106:107], v[232:233]
	v_pk_fma_f32 v[234:235], v[216:217], v[106:107], v[234:235]
	v_pk_fma_f32 v[236:237], v[216:217], v[102:103], v[236:237]
	v_pk_fma_f32 v[238:239], v[216:217], v[98:99], v[238:239]
	v_pk_fma_f32 v[234:235], v[218:219], v[102:103], v[234:235]
	v_pk_fma_f32 v[236:237], v[218:219], v[98:99], v[236:237]
	v_fmac_f32_dpp v232, v98, v214 row_shr:1 row_mask:0xf bank_mask:0xf bound_ctrl:1
	v_fmac_f32_dpp v233, v99, v215 row_shr:1 row_mask:0xf bank_mask:0xf bound_ctrl:1
	v_fmac_f32_dpp v238, v110, v218 row_shl:1 row_mask:0xf bank_mask:0xf bound_ctrl:1
	v_fmac_f32_dpp v239, v111, v219 row_shl:1 row_mask:0xf bank_mask:0xf bound_ctrl:1
	v_exp_f32_e64 v240, -v232
	v_pk_fma_f32 v[224:225], v[208:209], v[126:127], v[212:213]
	v_pk_fma_f32 v[226:227], v[206:207], v[126:127], v[212:213]
	v_exp_f32_e64 v241, -v233
	v_pk_fma_f32 v[228:229], v[206:207], v[122:123], v[212:213]
	v_pk_fma_f32 v[230:231], v[206:207], v[118:119], v[212:213]
	v_exp_f32_e64 v242, -v234
	v_pk_fma_f32 v[224:225], v[210:211], v[122:123], v[224:225]
	v_pk_fma_f32 v[226:227], v[208:209], v[122:123], v[226:227]
	v_exp_f32_e64 v243, -v235
	v_pk_fma_f32 v[228:229], v[208:209], v[118:119], v[228:229]
	v_pk_fma_f32 v[230:231], v[208:209], v[114:115], v[230:231]
	v_exp_f32_e64 v244, -v236
	v_pk_fma_f32 v[226:227], v[210:211], v[118:119], v[226:227]
	v_pk_fma_f32 v[228:229], v[210:211], v[114:115], v[228:229]
	v_exp_f32_e64 v245, -v237
	v_fmac_f32_dpp v224, v114, v206 row_shr:1 row_mask:0xf bank_mask:0xf bound_ctrl:1
	v_fmac_f32_dpp v225, v115, v207 row_shr:1 row_mask:0xf bank_mask:0xf bound_ctrl:1
	v_exp_f32_e64 v246, -v238
	v_fmac_f32_dpp v230, v126, v210 row_shl:1 row_mask:0xf bank_mask:0xf bound_ctrl:1
	v_fmac_f32_dpp v231, v127, v211 row_shl:1 row_mask:0xf bank_mask:0xf bound_ctrl:1
	v_exp_f32_e64 v247, -v239
	v_pk_add_f32 v[240:241], v[240:241], 1.0 op_sel_hi:[1,0]
	v_pk_add_f32 v[242:243], v[242:243], 1.0 op_sel_hi:[1,0]
	v_pk_add_f32 v[244:245], v[244:245], 1.0 op_sel_hi:[1,0]
	v_pk_add_f32 v[246:247], v[246:247], 1.0 op_sel_hi:[1,0]
	v_rcp_f32_e32 v240, v240
	v_pk_mul_f32 v[224:225], v[224:225], v[232:233]
	v_pk_mul_f32 v[226:227], v[226:227], v[234:235]
	v_rcp_f32_e32 v241, v241
	v_pk_mul_f32 v[228:229], v[228:229], v[236:237]
	v_pk_mul_f32 v[230:231], v[230:231], v[238:239]
	v_rcp_f32_e32 v242, v242
	v_pk_mul_f32 v[92:93], v[92:93], v[178:179] op_sel_hi:[1,0]
	v_pk_mul_f32 v[88:89], v[88:89], v[180:181] op_sel_hi:[1,0]
	v_rcp_f32_e32 v243, v243
	v_pk_mul_f32 v[84:85], v[84:85], v[182:183] op_sel_hi:[1,0]
	v_pk_mul_f32 v[80:81], v[80:81], v[144:145] op_sel_hi:[1,0]
	v_rcp_f32_e32 v244, v244
	v_pk_mul_f32 v[76:77], v[76:77], v[178:179] op_sel_hi:[1,0]
	v_pk_mul_f32 v[72:73], v[72:73], v[180:181] op_sel_hi:[1,0]
	v_rcp_f32_e32 v245, v245
	v_pk_mul_f32 v[68:69], v[68:69], v[182:183] op_sel_hi:[1,0]
	v_rcp_f32_e32 v246, v246
	v_pk_mul_f32 v[64:65], v[64:65], v[144:145] op_sel_hi:[1,0]
	v_rcp_f32_e32 v247, v247
	s_nop 0
	v_pk_mul_f32 v[224:225], v[224:225], v[240:241]
	v_pk_mul_f32 v[226:227], v[226:227], v[242:243]
	v_pk_mul_f32 v[228:229], v[228:229], v[244:245]
	v_pk_mul_f32 v[230:231], v[230:231], v[246:247]
	v_cvt_pk_bf16_f32 v129, v224, v225
	v_cvt_pk_bf16_f32 v133, v226, v227
	v_cvt_pk_bf16_f32 v137, v228, v229
	v_cvt_pk_bf16_f32 v141, v230, v231
	global_load_dwordx4 v[206:209], v172, s[64:65] offset:192
	global_load_dwordx4 v[210:213], v172, s[64:65] offset:208
	global_load_dwordx4 v[214:217], v172, s[64:65] offset:224
	global_load_dwordx4 v[218:221], v172, s[64:65] offset:240
	s_waitcnt vmcnt(4)
	v_pk_fma_f32 v[232:233], v[200:201], v[76:77], v[204:205]
	v_pk_fma_f32 v[234:235], v[198:199], v[76:77], v[204:205]
	v_pk_fma_f32 v[236:237], v[198:199], v[72:73], v[204:205]
	v_pk_fma_f32 v[238:239], v[198:199], v[68:69], v[204:205]
	v_pk_fma_f32 v[232:233], v[202:203], v[72:73], v[232:233]
	v_pk_fma_f32 v[234:235], v[200:201], v[72:73], v[234:235]
	v_pk_fma_f32 v[236:237], v[200:201], v[68:69], v[236:237]
	v_pk_fma_f32 v[238:239], v[200:201], v[64:65], v[238:239]
	v_pk_fma_f32 v[234:235], v[202:203], v[68:69], v[234:235]
	v_pk_fma_f32 v[236:237], v[202:203], v[64:65], v[236:237]
	v_fmac_f32_dpp v232, v64, v198 row_shr:1 row_mask:0xf bank_mask:0xf bound_ctrl:1
	v_fmac_f32_dpp v233, v65, v199 row_shr:1 row_mask:0xf bank_mask:0xf bound_ctrl:1
	v_fmac_f32_dpp v238, v76, v202 row_shl:1 row_mask:0xf bank_mask:0xf bound_ctrl:1
	v_fmac_f32_dpp v239, v77, v203 row_shl:1 row_mask:0xf bank_mask:0xf bound_ctrl:1
	v_exp_f32_e64 v240, -v232
	v_pk_fma_f32 v[224:225], v[192:193], v[92:93], v[196:197]
	v_pk_fma_f32 v[226:227], v[190:191], v[92:93], v[196:197]
	v_exp_f32_e64 v241, -v233
	v_pk_fma_f32 v[228:229], v[190:191], v[88:89], v[196:197]
	v_pk_fma_f32 v[230:231], v[190:191], v[84:85], v[196:197]
	v_exp_f32_e64 v242, -v234
	v_pk_fma_f32 v[224:225], v[194:195], v[88:89], v[224:225]
	v_pk_fma_f32 v[226:227], v[192:193], v[88:89], v[226:227]
	v_exp_f32_e64 v243, -v235
	v_pk_fma_f32 v[228:229], v[192:193], v[84:85], v[228:229]
	v_pk_fma_f32 v[230:231], v[192:193], v[80:81], v[230:231]
	v_exp_f32_e64 v244, -v236
	v_pk_fma_f32 v[226:227], v[194:195], v[84:85], v[226:227]
	v_pk_fma_f32 v[228:229], v[194:195], v[80:81], v[228:229]
	v_exp_f32_e64 v245, -v237
	v_fmac_f32_dpp v224, v80, v190 row_shr:1 row_mask:0xf bank_mask:0xf bound_ctrl:1
	v_fmac_f32_dpp v225, v81, v191 row_shr:1 row_mask:0xf bank_mask:0xf bound_ctrl:1
;     __device__ __forceinline__ void operator()(const f32x4 (&acc)[2][2][4][2], const Unit& u, int wr, int wc, int fr, int fq) const {
;     ...
;             for (int m = 0; m < 4; ++m) { const int t = tbase + 16 * m + fr; const bool vin = (t >= 0) && (t < slen); const int grow = seqbase + (vin ? t : 0);
;                 const f32x4 p = *(const f32x4*)(PS + (size_t)grow * 16 + 4 * fq); float s = (p[0] + p[1]) + (p[2] + p[3]); s = bfly_add<16>(s); s = bfly_add<32>(s); rs[m] = vin ? rsqrtf(s * (1.f / DM) + EPS) : 0.f; }
;             unsigned outw[4][2][2];
; #pragma unroll
;             for (int n = 0; n < 2; ++n)
; #pragma unroll
;                 for (int jp = 0; jp < 2; ++jp) {
;                     const int cidx = (4 * n + 2 * jp) * 2;
;                     const f32x4 c0a = ct[cidx], c0b = ct[cidx + 1], c1a = ct[cidx + 2], c1b = ct[cidx + 3];
;                     const f32x2 wv0 = {c0a[0], c1a[0]}, wv1 = {c0a[1], c1a[1]}, wv2 = {c0a[2], c1a[2]}, bv = {c0a[3], c1a[3]};
;                     const f32x2 wg0 = {c0b[0], c1b[0]}, wg1 = {c0b[1], c1b[1]}, wg2 = {c0b[2], c1b[2]}, bg = {c0b[3], c1b[3]};
;                     f32x2 uv[4], ug[4], cv[4];
; #pragma unroll
;                     for (int m = 0; m < 4; ++m) { uv[m] = (f32x2){acc[ai][0][m][n][2 * jp], acc[ai][0][m][n][2 * jp + 1]}; ug[m] = (f32x2){acc[ai][1][m][n][2 * jp], acc[ai][1][m][n][2 * jp + 1]}; }
;                     asm volatile("" : "+v"(uv[0]), "+v"(uv[1]), "+v"(uv[2]), "+v"(uv[3]), "+v"(ug[0]), "+v"(ug[1]), "+v"(ug[2]), "+v"(ug[3]));
;                     {
;                         f32x2 rv[4], lv[4];
; #pragma unroll
;                         for (int m = 0; m < 4; ++m) { uv[m] = uv[m] * rs[m]; rv[m] = (f32x2){dpp_ror1(uv[m][0]), dpp_ror1(uv[m][1])}; lv[m] = (f32x2){dpp_ror15(uv[m][0]), dpp_ror15(uv[m][1])}; }
; #pragma unroll
;                         for (int m = 0; m < 4; ++m) { const f32x2 pv_ = (m > 0 && f0) ? rv[m > 0 ? m - 1 : 0] : rv[m], nv_ = (m < 3 && f15) ? lv[m < 3 ? m + 1 : 3] : lv[m];
;                             cv[m] = bv + wv0 * pv_ + wv1 * uv[m] + wv2 * nv_; }
;                     }
;                     asm volatile("" : "+v"(cv[0]), "+v"(cv[1]), "+v"(cv[2]), "+v"(cv[3]));
;                     {
;                         f32x2 rg[4], lg[4];
; #pragma unroll
	v_exp_f32_e64 v246, -v238
	v_fmac_f32_dpp v230, v92, v194 row_shl:1 row_mask:0xf bank_mask:0xf bound_ctrl:1
	v_fmac_f32_dpp v231, v93, v195 row_shl:1 row_mask:0xf bank_mask:0xf bound_ctrl:1
	v_exp_f32_e64 v247, -v239
	v_pk_add_f32 v[240:241], v[240:241], 1.0 op_sel_hi:[1,0]
	v_pk_add_f32 v[242:243], v[242:243], 1.0 op_sel_hi:[1,0]
	v_pk_add_f32 v[244:245], v[244:245], 1.0 op_sel_hi:[1,0]
	v_pk_add_f32 v[246:247], v[246:247], 1.0 op_sel_hi:[1,0]
	v_rcp_f32_e32 v240, v240
	v_pk_mul_f32 v[224:225], v[224:225], v[232:233]
	v_pk_mul_f32 v[226:227], v[226:227], v[234:235]
	v_rcp_f32_e32 v241, v241
	v_pk_mul_f32 v[228:229], v[228:229], v[236:237]
	v_pk_mul_f32 v[230:231], v[230:231], v[238:239]
	v_rcp_f32_e32 v242, v242
	v_pk_mul_f32 v[94:95], v[94:95], v[178:179] op_sel_hi:[1,0]
	v_pk_mul_f32 v[90:91], v[90:91], v[180:181] op_sel_hi:[1,0]
	v_rcp_f32_e32 v243, v243
	v_pk_mul_f32 v[86:87], v[86:87], v[182:183] op_sel_hi:[1,0]
	v_pk_mul_f32 v[82:83], v[82:83], v[144:145] op_sel_hi:[1,0]
	v_rcp_f32_e32 v244, v244
	v_pk_mul_f32 v[78:79], v[78:79], v[178:179] op_sel_hi:[1,0]
	v_pk_mul_f32 v[74:75], v[74:75], v[180:181] op_sel_hi:[1,0]
	v_rcp_f32_e32 v245, v245
	v_pk_mul_f32 v[70:71], v[70:71], v[182:183] op_sel_hi:[1,0]
	v_rcp_f32_e32 v246, v246
	v_pk_mul_f32 v[66:67], v[66:67], v[144:145] op_sel_hi:[1,0]
	v_rcp_f32_e32 v247, v247
	s_nop 0
	v_pk_mul_f32 v[224:225], v[224:225], v[240:241]
	v_pk_mul_f32 v[226:227], v[226:227], v[242:243]
	v_pk_mul_f32 v[228:229], v[228:229], v[244:245]
	v_pk_mul_f32 v[230:231], v[230:231], v[246:247]
	v_cvt_pk_bf16_f32 v130, v224, v225
	v_cvt_pk_bf16_f32 v134, v226, v227
	v_cvt_pk_bf16_f32 v138, v228, v229
	v_cvt_pk_bf16_f32 v142, v230, v231
	s_waitcnt vmcnt(0)
	v_add_u32_e32 v253, 0x7c, v174
	v_lshrrev_b32_e32 v176, 4, v165
	v_add_u32_e32 v176, v176, v253
	v_cmp_gt_u32_e32 vcc, s91, v176
	s_nop 1
	v_cndmask_b32_e32 v176, 0, v176, vcc
	v_add_u32_e32 v176, s88, v176
	v_lshlrev_b32_e32 v248, 6, v176
	global_load_dwordx4 v[190:193], v248, s[70:71]
	global_load_dwordx4 v[194:197], v248, s[70:71] offset:16
	global_load_dwordx4 v[198:201], v248, s[70:71] offset:32
	global_load_dwordx4 v[202:205], v248, s[70:71] offset:48
	v_pk_fma_f32 v[232:233], v[216:217], v[78:79], v[220:221]
	v_pk_fma_f32 v[234:235], v[214:215], v[78:79], v[220:221]
	v_pk_fma_f32 v[236:237], v[214:215], v[74:75], v[220:221]
	v_pk_fma_f32 v[238:239], v[214:215], v[70:71], v[220:221]
	v_pk_fma_f32 v[232:233], v[218:219], v[74:75], v[232:233]
	v_pk_fma_f32 v[234:235], v[216:217], v[74:75], v[234:235]
	v_pk_fma_f32 v[236:237], v[216:217], v[70:71], v[236:237]
	v_pk_fma_f32 v[238:239], v[216:217], v[66:67], v[238:239]
	v_pk_fma_f32 v[234:235], v[218:219], v[70:71], v[234:235]
	v_pk_fma_f32 v[236:237], v[218:219], v[66:67], v[236:237]
	v_fmac_f32_dpp v232, v66, v214 row_shr:1 row_mask:0xf bank_mask:0xf bound_ctrl:1
	v_fmac_f32_dpp v233, v67, v215 row_shr:1 row_mask:0xf bank_mask:0xf bound_ctrl:1
	v_fmac_f32_dpp v238, v78, v218 row_shl:1 row_mask:0xf bank_mask:0xf bound_ctrl:1
	v_fmac_f32_dpp v239, v79, v219 row_shl:1 row_mask:0xf bank_mask:0xf bound_ctrl:1
	v_exp_f32_e64 v240, -v232
	v_pk_fma_f32 v[224:225], v[208:209], v[94:95], v[212:213]
	v_pk_fma_f32 v[226:227], v[206:207], v[94:95], v[212:213]
	v_exp_f32_e64 v241, -v233
	v_pk_fma_f32 v[228:229], v[206:207], v[90:91], v[212:213]
	v_pk_fma_f32 v[230:231], v[206:207], v[86:87], v[212:213]
	v_exp_f32_e64 v242, -v234
	v_pk_fma_f32 v[224:225], v[210:211], v[90:91], v[224:225]
	v_pk_fma_f32 v[226:227], v[208:209], v[90:91], v[226:227]
	v_exp_f32_e64 v243, -v235
	v_pk_fma_f32 v[228:229], v[208:209], v[86:87], v[228:229]
	v_pk_fma_f32 v[230:231], v[208:209], v[82:83], v[230:231]
	v_exp_f32_e64 v244, -v236
	v_pk_fma_f32 v[226:227], v[210:211], v[86:87], v[226:227]
	v_pk_fma_f32 v[228:229], v[210:211], v[82:83], v[228:229]
	v_exp_f32_e64 v245, -v237
	v_fmac_f32_dpp v224, v82, v206 row_shr:1 row_mask:0xf bank_mask:0xf bound_ctrl:1
	v_fmac_f32_dpp v225, v83, v207 row_shr:1 row_mask:0xf bank_mask:0xf bound_ctrl:1
	v_exp_f32_e64 v246, -v238
	v_fmac_f32_dpp v230, v94, v210 row_shl:1 row_mask:0xf bank_mask:0xf bound_ctrl:1
	v_fmac_f32_dpp v231, v95, v211 row_shl:1 row_mask:0xf bank_mask:0xf bound_ctrl:1
	v_exp_f32_e64 v247, -v239
	v_pk_add_f32 v[240:241], v[240:241], 1.0 op_sel_hi:[1,0]
	v_pk_add_f32 v[242:243], v[242:243], 1.0 op_sel_hi:[1,0]
	v_pk_add_f32 v[244:245], v[244:245], 1.0 op_sel_hi:[1,0]
	v_pk_add_f32 v[246:247], v[246:247], 1.0 op_sel_hi:[1,0]
	v_rcp_f32_e32 v240, v240
	v_pk_mul_f32 v[224:225], v[224:225], v[232:233]
	v_rcp_f32_e32 v241, v241
	v_pk_mul_f32 v[226:227], v[226:227], v[234:235]
	v_rcp_f32_e32 v242, v242
	v_pk_mul_f32 v[228:229], v[228:229], v[236:237]
	v_rcp_f32_e32 v243, v243
	v_pk_mul_f32 v[230:231], v[230:231], v[238:239]
	v_rcp_f32_e32 v244, v244
	v_rcp_f32_e32 v245, v245
	v_rcp_f32_e32 v246, v246
	v_rcp_f32_e32 v247, v247
	s_nop 0
	v_pk_mul_f32 v[224:225], v[224:225], v[240:241]
	v_pk_mul_f32 v[226:227], v[226:227], v[242:243]
	v_pk_mul_f32 v[228:229], v[228:229], v[244:245]
	v_pk_mul_f32 v[230:231], v[230:231], v[246:247]
	v_cvt_pk_bf16_f32 v131, v224, v225
	v_cvt_pk_bf16_f32 v135, v226, v227
	v_cvt_pk_bf16_f32 v139, v228, v229
	v_cvt_pk_bf16_f32 v143, v230, v231
	s_sub_i32 s51, s91, s89
	s_sub_i32 s66, s51, 4
	s_max_i32 s66, s66, 0
	v_add_u32_e32 v176, -4, v164
	v_cmp_gt_u32_e32 vcc, s66, v176
	v_add_u32_e32 v176, 0, v174
	v_add_u32_e32 v176, s88, v176
	v_mad_u32_u24 v248, v176, s54, v165
	s_mov_b64 exec, vcc
	global_store_dwordx4 v248, v[128:131], s[86:87]
	s_mov_b64 exec, -1
	s_sub_i32 s66, s51, 1
	s_max_i32 s66, s66, 0
	v_cmp_gt_u32_e32 vcc, s66, v164
	v_add_u32_e32 v176, 1, v174
	v_add_u32_e32 v176, s88, v176
	v_mad_u32_u24 v249, v176, s54, v165
	s_mov_b64 exec, vcc
	global_store_dwordx4 v249, v[132:135], s[86:87]
	s_mov_b64 exec, -1
	s_sub_i32 s66, s51, 2
	s_max_i32 s66, s66, 0
	v_cmp_gt_u32_e32 vcc, s66, v164
	v_add_u32_e32 v176, 2, v174
	v_add_u32_e32 v176, s88, v176
	v_mad_u32_u24 v250, v176, s54, v165
	s_mov_b64 exec, vcc
	global_store_dwordx4 v250, v[136:139], s[86:87]
	s_mov_b64 exec, -1
	s_sub_i32 s66, s51, 3
	s_min_i32 s66, s66, 60
	s_max_i32 s66, s66, 0
	v_cmp_gt_u32_e32 vcc, s66, v164
	v_add_u32_e32 v176, 3, v174
	v_add_u32_e32 v176, s88, v176
	v_mad_u32_u24 v251, v176, s54, v165
	s_mov_b64 exec, vcc
	global_store_dwordx4 v251, v[140:143], s[86:87]
	s_mov_b64 exec, -1
	s_addk_i32 s89, 0x7c
	v_mov_b32_e32 v174, v253
	global_load_dwordx4 v[206:209], v172, s[64:65]
	global_load_dwordx4 v[210:213], v172, s[64:65] offset:16
	global_load_dwordx4 v[214:217], v172, s[64:65] offset:32
	global_load_dwordx4 v[218:221], v172, s[64:65] offset:48
	v_lshrrev_b32_e32 v176, 4, v165
	v_add_u32_e32 v176, v176, v174
	v_cmp_gt_u32_e32 vcc, s91, v176
	s_waitcnt vmcnt(8)
;     __device__ __forceinline__ void operator()(const f32x4 (&acc)[2][2][4][2], const Unit& u, int wr, int wc, int fr, int fq) const {
;     ...
;             for (int m = 0; m < 4; ++m) { const int t = tbase + 16 * m + fr; const bool vin = (t >= 0) && (t < slen); const int grow = seqbase + (vin ? t : 0);
;                 const f32x4 p = *(const f32x4*)(PS + (size_t)grow * 16 + 4 * fq); float s = (p[0] + p[1]) + (p[2] + p[3]); s = bfly_add<16>(s); s = bfly_add<32>(s); rs[m] = vin ? rsqrtf(s * (1.f / DM) + EPS) : 0.f; }
;             unsigned outw[4][2][2];
; #pragma unroll
;             for (int n = 0; n < 2; ++n)
; #pragma unroll
;                 for (int jp = 0; jp < 2; ++jp) {
;                     const int cidx = (4 * n + 2 * jp) * 2;
;                     const f32x4 c0a = ct[cidx], c0b = ct[cidx + 1], c1a = ct[cidx + 2], c1b = ct[cidx + 3];
;                     const f32x2 wv0 = {c0a[0], c1a[0]}, wv1 = {c0a[1], c1a[1]}, wv2 = {c0a[2], c1a[2]}, bv = {c0a[3], c1a[3]};
;                     const f32x2 wg0 = {c0b[0], c1b[0]}, wg1 = {c0b[1], c1b[1]}, wg2 = {c0b[2], c1b[2]}, bg = {c0b[3], c1b[3]};
;                     f32x2 uv[4], ug[4], cv[4];
; #pragma unroll
;                     for (int m = 0; m < 4; ++m) { uv[m] = (f32x2){acc[ai][0][m][n][2 * jp], acc[ai][0][m][n][2 * jp + 1]}; ug[m] = (f32x2){acc[ai][1][m][n][2 * jp], acc[ai][1][m][n][2 * jp + 1]}; }
;                     asm volatile("" : "+v"(uv[0]), "+v"(uv[1]), "+v"(uv[2]), "+v"(uv[3]), "+v"(ug[0]), "+v"(ug[1]), "+v"(ug[2]), "+v"(ug[3]));
;                     {
;                         f32x2 rv[4], lv[4];
; #pragma unroll
;                         for (int m = 0; m < 4; ++m) { uv[m] = uv[m] * rs[m]; rv[m] = (f32x2){dpp_ror1(uv[m][0]), dpp_ror1(uv[m][1])}; lv[m] = (f32x2){dpp_ror15(uv[m][0]), dpp_ror15(uv[m][1])}; }
; #pragma unroll
;                         for (int m = 0; m < 4; ++m) { const f32x2 pv_ = (m > 0 && f0) ? rv[m > 0 ? m - 1 : 0] : rv[m], nv_ = (m < 3 && f15) ? lv[m < 3 ? m + 1 : 3] : lv[m];
;                             cv[m] = bv + wv0 * pv_ + wv1 * uv[m] + wv2 * nv_; }
;                     }
;                     asm volatile("" : "+v"(cv[0]), "+v"(cv[1]), "+v"(cv[2]), "+v"(cv[3]));
;                     {
;                         f32x2 rg[4], lg[4];
; #pragma unroll
	v_pk_add_f32 v[190:191], v[190:191], v[194:195]
	v_pk_add_f32 v[192:193], v[192:193], v[196:197]
	v_pk_add_f32 v[198:199], v[198:199], v[202:203]
	v_pk_add_f32 v[200:201], v[200:201], v[204:205]
	v_pk_add_f32 v[190:191], v[190:191], v[198:199]
	v_pk_add_f32 v[192:193], v[192:193], v[200:201]
	v_pk_add_f32 v[190:191], v[190:191], v[192:193]
	v_add_f32_e32 v190, v190, v191
	v_fma_f32 v190, v190, s82, v252
	v_rsq_f32_e32 v190, v190
	s_nop 0
	v_cndmask_b32_e32 v178, 0, v190, vcc
	v_mov_b32_e32 v180, v178
	s_nop 1
	v_permlane16_swap_b32_e32 v178, v180
	v_mov_b32_e32 v182, v178
	v_mov_b32_e32 v144, v180
	s_nop 1
	v_permlane32_swap_b32_e32 v178, v182
	v_permlane32_swap_b32_e32 v180, v144
	v_pk_mul_f32 v[60:61], v[60:61], v[178:179] op_sel_hi:[1,0]
	v_pk_mul_f32 v[56:57], v[56:57], v[180:181] op_sel_hi:[1,0]
	v_pk_mul_f32 v[52:53], v[52:53], v[182:183] op_sel_hi:[1,0]
	v_pk_mul_f32 v[48:49], v[48:49], v[144:145] op_sel_hi:[1,0]
	v_pk_mul_f32 v[44:45], v[44:45], v[178:179] op_sel_hi:[1,0]
	v_pk_mul_f32 v[40:41], v[40:41], v[180:181] op_sel_hi:[1,0]
	v_pk_mul_f32 v[36:37], v[36:37], v[182:183] op_sel_hi:[1,0]
	v_pk_mul_f32 v[32:33], v[32:33], v[144:145] op_sel_hi:[1,0]
	global_load_dwordx4 v[190:193], v172, s[64:65] offset:64
	global_load_dwordx4 v[194:197], v172, s[64:65] offset:80
	global_load_dwordx4 v[198:201], v172, s[64:65] offset:96
	global_load_dwordx4 v[202:205], v172, s[64:65] offset:112
	s_waitcnt vmcnt(4)
	v_pk_fma_f32 v[232:233], v[216:217], v[44:45], v[220:221]
	v_pk_fma_f32 v[234:235], v[214:215], v[44:45], v[220:221]
	v_pk_fma_f32 v[236:237], v[214:215], v[40:41], v[220:221]
	v_pk_fma_f32 v[238:239], v[214:215], v[36:37], v[220:221]
	v_pk_fma_f32 v[232:233], v[218:219], v[40:41], v[232:233]
	v_pk_fma_f32 v[234:235], v[216:217], v[40:41], v[234:235]
	v_pk_fma_f32 v[236:237], v[216:217], v[36:37], v[236:237]
	v_pk_fma_f32 v[238:239], v[216:217], v[32:33], v[238:239]
	v_pk_fma_f32 v[234:235], v[218:219], v[36:37], v[234:235]
	v_pk_fma_f32 v[236:237], v[218:219], v[32:33], v[236:237]
	v_fmac_f32_dpp v232, v32, v214 row_shr:1 row_mask:0xf bank_mask:0xf bound_ctrl:1
	v_fmac_f32_dpp v233, v33, v215 row_shr:1 row_mask:0xf bank_mask:0xf bound_ctrl:1
	v_fmac_f32_dpp v238, v44, v218 row_shl:1 row_mask:0xf bank_mask:0xf bound_ctrl:1
	v_fmac_f32_dpp v239, v45, v219 row_shl:1 row_mask:0xf bank_mask:0xf bound_ctrl:1
	v_exp_f32_e64 v240, -v232
	v_pk_fma_f32 v[224:225], v[208:209], v[60:61], v[212:213]
	v_pk_fma_f32 v[226:227], v[206:207], v[60:61], v[212:213]
	v_exp_f32_e64 v241, -v233
	v_pk_fma_f32 v[228:229], v[206:207], v[56:57], v[212:213]
	v_pk_fma_f32 v[230:231], v[206:207], v[52:53], v[212:213]
	v_exp_f32_e64 v242, -v234
	v_pk_fma_f32 v[224:225], v[210:211], v[56:57], v[224:225]
	v_pk_fma_f32 v[226:227], v[208:209], v[56:57], v[226:227]
	v_exp_f32_e64 v243, -v235
	v_pk_fma_f32 v[228:229], v[208:209], v[52:53], v[228:229]
	v_pk_fma_f32 v[230:231], v[208:209], v[48:49], v[230:231]
	v_exp_f32_e64 v244, -v236
	v_pk_fma_f32 v[226:227], v[210:211], v[52:53], v[226:227]
	v_pk_fma_f32 v[228:229], v[210:211], v[48:49], v[228:229]
	v_exp_f32_e64 v245, -v237
	v_fmac_f32_dpp v224, v48, v206 row_shr:1 row_mask:0xf bank_mask:0xf bound_ctrl:1
	v_fmac_f32_dpp v225, v49, v207 row_shr:1 row_mask:0xf bank_mask:0xf bound_ctrl:1
	v_exp_f32_e64 v246, -v238
	v_fmac_f32_dpp v230, v60, v210 row_shl:1 row_mask:0xf bank_mask:0xf bound_ctrl:1
	v_fmac_f32_dpp v231, v61, v211 row_shl:1 row_mask:0xf bank_mask:0xf bound_ctrl:1
	v_exp_f32_e64 v247, -v239
	v_pk_add_f32 v[240:241], v[240:241], 1.0 op_sel_hi:[1,0]
	v_pk_add_f32 v[242:243], v[242:243], 1.0 op_sel_hi:[1,0]
	v_pk_add_f32 v[244:245], v[244:245], 1.0 op_sel_hi:[1,0]
	v_pk_add_f32 v[246:247], v[246:247], 1.0 op_sel_hi:[1,0]
	v_rcp_f32_e32 v240, v240
	v_pk_mul_f32 v[224:225], v[224:225], v[232:233]
	v_pk_mul_f32 v[226:227], v[226:227], v[234:235]
	v_rcp_f32_e32 v241, v241
	v_pk_mul_f32 v[228:229], v[228:229], v[236:237]
	v_pk_mul_f32 v[230:231], v[230:231], v[238:239]
	v_rcp_f32_e32 v242, v242
	v_pk_mul_f32 v[62:63], v[62:63], v[178:179] op_sel_hi:[1,0]
	v_pk_mul_f32 v[58:59], v[58:59], v[180:181] op_sel_hi:[1,0]
	v_rcp_f32_e32 v243, v243
	v_pk_mul_f32 v[54:55], v[54:55], v[182:183] op_sel_hi:[1,0]
	v_pk_mul_f32 v[50:51], v[50:51], v[144:145] op_sel_hi:[1,0]
	v_rcp_f32_e32 v244, v244
	v_pk_mul_f32 v[46:47], v[46:47], v[178:179] op_sel_hi:[1,0]
	v_pk_mul_f32 v[42:43], v[42:43], v[180:181] op_sel_hi:[1,0]
	v_rcp_f32_e32 v245, v245
	v_pk_mul_f32 v[38:39], v[38:39], v[182:183] op_sel_hi:[1,0]
	v_rcp_f32_e32 v246, v246
	v_pk_mul_f32 v[34:35], v[34:35], v[144:145] op_sel_hi:[1,0]
	v_rcp_f32_e32 v247, v247
	s_nop 0
	v_pk_mul_f32 v[224:225], v[224:225], v[240:241]
	v_pk_mul_f32 v[226:227], v[226:227], v[242:243]
	v_pk_mul_f32 v[228:229], v[228:229], v[244:245]
	v_pk_mul_f32 v[230:231], v[230:231], v[246:247]
	v_cvt_pk_bf16_f32 v128, v224, v225
	v_cvt_pk_bf16_f32 v132, v226, v227
	v_cvt_pk_bf16_f32 v136, v228, v229
	v_cvt_pk_bf16_f32 v140, v230, v231
	global_load_dwordx4 v[206:209], v172, s[64:65] offset:128
	global_load_dwordx4 v[210:213], v172, s[64:65] offset:144
	global_load_dwordx4 v[214:217], v172, s[64:65] offset:160
	global_load_dwordx4 v[218:221], v172, s[64:65] offset:176
	s_waitcnt vmcnt(4)
;     __device__ __forceinline__ void operator()(const f32x4 (&acc)[2][2][4][2], const Unit& u, int wr, int wc, int fr, int fq) const {
;     ...
;                     const f32x4 c0a = ct[cidx], c0b = ct[cidx + 1], c1a = ct[cidx + 2], c1b = ct[cidx + 3];
;                     const f32x2 wv0 = {c0a[0], c1a[0]}, wv1 = {c0a[1], c1a[1]}, wv2 = {c0a[2], c1a[2]}, bv = {c0a[3], c1a[3]};
;                     const f32x2 wg0 = {c0b[0], c1b[0]}, wg1 = {c0b[1], c1b[1]}, wg2 = {c0b[2], c1b[2]}, bg = {c0b[3], c1b[3]};
;                     f32x2 uv[4], ug[4], cv[4];
; #pragma unroll
;                     for (int m = 0; m < 4; ++m) { uv[m] = (f32x2){acc[ai][0][m][n][2 * jp], acc[ai][0][m][n][2 * jp + 1]}; ug[m] = (f32x2){acc[ai][1][m][n][2 * jp], acc[ai][1][m][n][2 * jp + 1]}; }
;                     asm volatile("" : "+v"(uv[0]), "+v"(uv[1]), "+v"(uv[2]), "+v"(uv[3]), "+v"(ug[0]), "+v"(ug[1]), "+v"(ug[2]), "+v"(ug[3]));
;                     {
;                         f32x2 rv[4], lv[4];
; #pragma unroll
;                         for (int m = 0; m < 4; ++m) { uv[m] = uv[m] * rs[m]; rv[m] = (f32x2){dpp_ror1(uv[m][0]), dpp_ror1(uv[m][1])}; lv[m] = (f32x2){dpp_ror15(uv[m][0]), dpp_ror15(uv[m][1])}; }
; #pragma unroll
;                         for (int m = 0; m < 4; ++m) { const f32x2 pv_ = (m > 0 && f0) ? rv[m > 0 ? m - 1 : 0] : rv[m], nv_ = (m < 3 && f15) ? lv[m < 3 ? m + 1 : 3] : lv[m];
;                             cv[m] = bv + wv0 * pv_ + wv1 * uv[m] + wv2 * nv_; }
;                     }
;                     asm volatile("" : "+v"(cv[0]), "+v"(cv[1]), "+v"(cv[2]), "+v"(cv[3]));
;                     {
;                         f32x2 rg[4], lg[4];
; #pragma unroll
;                         for (int m = 0; m < 4; ++m) { ug[m] = ug[m] * rs[m]; rg[m] = (f32x2){dpp_ror1(ug[m][0]), dpp_ror1(ug[m][1])}; lg[m] = (f32x2){dpp_ror15(ug[m][0]), dpp_ror15(ug[m][1])}; }
; #pragma unroll
;                         for (int m = 0; m < 4; ++m) { const f32x2 pg_ = (m > 0 && f0) ? rg[m > 0 ? m - 1 : 0] : rg[m], ng_ = (m < 3 && f15) ? lg[m < 3 ? m + 1 : 3] : lg[m];
;                             const f32x2 cgt = bg + wg0 * pg_ + wg1 * ug[m] + wg2 * ng_;
;                             const f32x2 e = cgt * (-LOG2E);
;                             const f32x2 d = (f32x2){__builtin_amdgcn_exp2f(e[0]), __builtin_amdgcn_exp2f(e[1])} + 1.f;
	v_pk_fma_f32 v[232:233], v[200:201], v[46:47], v[204:205]
	v_pk_fma_f32 v[234:235], v[198:199], v[46:47], v[204:205]
	v_pk_fma_f32 v[236:237], v[198:199], v[42:43], v[204:205]
	v_pk_fma_f32 v[238:239], v[198:199], v[38:39], v[204:205]
	v_pk_fma_f32 v[232:233], v[202:203], v[42:43], v[232:233]
	v_pk_fma_f32 v[234:235], v[200:201], v[42:43], v[234:235]
	v_pk_fma_f32 v[236:237], v[200:201], v[38:39], v[236:237]
	v_pk_fma_f32 v[238:239], v[200:201], v[34:35], v[238:239]
	v_pk_fma_f32 v[234:235], v[202:203], v[38:39], v[234:235]
	v_pk_fma_f32 v[236:237], v[202:203], v[34:35], v[236:237]
	v_fmac_f32_dpp v232, v34, v198 row_shr:1 row_mask:0xf bank_mask:0xf bound_ctrl:1
	v_fmac_f32_dpp v233, v35, v199 row_shr:1 row_mask:0xf bank_mask:0xf bound_ctrl:1
	v_fmac_f32_dpp v238, v46, v202 row_shl:1 row_mask:0xf bank_mask:0xf bound_ctrl:1
	v_fmac_f32_dpp v239, v47, v203 row_shl:1 row_mask:0xf bank_mask:0xf bound_ctrl:1
	v_exp_f32_e64 v240, -v232
	v_pk_fma_f32 v[224:225], v[192:193], v[62:63], v[196:197]
	v_pk_fma_f32 v[226:227], v[190:191], v[62:63], v[196:197]
	v_exp_f32_e64 v241, -v233
	v_pk_fma_f32 v[228:229], v[190:191], v[58:59], v[196:197]
	v_pk_fma_f32 v[230:231], v[190:191], v[54:55], v[196:197]
	v_exp_f32_e64 v242, -v234
	v_pk_fma_f32 v[224:225], v[194:195], v[58:59], v[224:225]
	v_pk_fma_f32 v[226:227], v[192:193], v[58:59], v[226:227]
	v_exp_f32_e64 v243, -v235
	v_pk_fma_f32 v[228:229], v[192:193], v[54:55], v[228:229]
	v_pk_fma_f32 v[230:231], v[192:193], v[50:51], v[230:231]
	v_exp_f32_e64 v244, -v236
	v_pk_fma_f32 v[226:227], v[194:195], v[54:55], v[226:227]
	v_pk_fma_f32 v[228:229], v[194:195], v[50:51], v[228:229]
	v_exp_f32_e64 v245, -v237
	v_fmac_f32_dpp v224, v50, v190 row_shr:1 row_mask:0xf bank_mask:0xf bound_ctrl:1
	v_fmac_f32_dpp v225, v51, v191 row_shr:1 row_mask:0xf bank_mask:0xf bound_ctrl:1
	v_exp_f32_e64 v246, -v238
	v_fmac_f32_dpp v230, v62, v194 row_shl:1 row_mask:0xf bank_mask:0xf bound_ctrl:1
	v_fmac_f32_dpp v231, v63, v195 row_shl:1 row_mask:0xf bank_mask:0xf bound_ctrl:1
	v_exp_f32_e64 v247, -v239
	v_pk_add_f32 v[240:241], v[240:241], 1.0 op_sel_hi:[1,0]
	v_pk_add_f32 v[242:243], v[242:243], 1.0 op_sel_hi:[1,0]
	v_pk_add_f32 v[244:245], v[244:245], 1.0 op_sel_hi:[1,0]
	v_pk_add_f32 v[246:247], v[246:247], 1.0 op_sel_hi:[1,0]
	v_rcp_f32_e32 v240, v240
	v_pk_mul_f32 v[224:225], v[224:225], v[232:233]
	v_pk_mul_f32 v[226:227], v[226:227], v[234:235]
	v_rcp_f32_e32 v241, v241
	v_pk_mul_f32 v[228:229], v[228:229], v[236:237]
	v_pk_mul_f32 v[230:231], v[230:231], v[238:239]
	v_rcp_f32_e32 v242, v242
	v_pk_mul_f32 v[28:29], v[28:29], v[178:179] op_sel_hi:[1,0]
	v_pk_mul_f32 v[24:25], v[24:25], v[180:181] op_sel_hi:[1,0]
	v_rcp_f32_e32 v243, v243
	v_pk_mul_f32 v[20:21], v[20:21], v[182:183] op_sel_hi:[1,0]
	v_pk_mul_f32 v[16:17], v[16:17], v[144:145] op_sel_hi:[1,0]
	v_rcp_f32_e32 v244, v244
	v_pk_mul_f32 v[12:13], v[12:13], v[178:179] op_sel_hi:[1,0]
	v_pk_mul_f32 v[8:9], v[8:9], v[180:181] op_sel_hi:[1,0]
	v_rcp_f32_e32 v245, v245
	v_pk_mul_f32 v[4:5], v[4:5], v[182:183] op_sel_hi:[1,0]
	v_rcp_f32_e32 v246, v246
	v_pk_mul_f32 v[0:1], v[0:1], v[144:145] op_sel_hi:[1,0]
	v_rcp_f32_e32 v247, v247
	s_nop 0
	v_pk_mul_f32 v[224:225], v[224:225], v[240:241]
	v_pk_mul_f32 v[226:227], v[226:227], v[242:243]
	v_pk_mul_f32 v[228:229], v[228:229], v[244:245]
	v_pk_mul_f32 v[230:231], v[230:231], v[246:247]
	v_cvt_pk_bf16_f32 v129, v224, v225
	v_cvt_pk_bf16_f32 v133, v226, v227
	v_cvt_pk_bf16_f32 v137, v228, v229
	v_cvt_pk_bf16_f32 v141, v230, v231
	global_load_dwordx4 v[190:193], v172, s[64:65] offset:192
	global_load_dwordx4 v[194:197], v172, s[64:65] offset:208
	global_load_dwordx4 v[198:201], v172, s[64:65] offset:224
	global_load_dwordx4 v[202:205], v172, s[64:65] offset:240
	s_waitcnt vmcnt(4)
	v_pk_fma_f32 v[232:233], v[216:217], v[12:13], v[220:221]
	v_pk_fma_f32 v[234:235], v[214:215], v[12:13], v[220:221]
	v_pk_fma_f32 v[236:237], v[214:215], v[8:9], v[220:221]
	v_pk_fma_f32 v[238:239], v[214:215], v[4:5], v[220:221]
	v_pk_fma_f32 v[232:233], v[218:219], v[8:9], v[232:233]
	v_pk_fma_f32 v[234:235], v[216:217], v[8:9], v[234:235]
	v_pk_fma_f32 v[236:237], v[216:217], v[4:5], v[236:237]
	v_pk_fma_f32 v[238:239], v[216:217], v[0:1], v[238:239]
	v_pk_fma_f32 v[234:235], v[218:219], v[4:5], v[234:235]
	v_pk_fma_f32 v[236:237], v[218:219], v[0:1], v[236:237]
	v_fmac_f32_dpp v232, v0, v214 row_shr:1 row_mask:0xf bank_mask:0xf bound_ctrl:1
	v_fmac_f32_dpp v233, v1, v215 row_shr:1 row_mask:0xf bank_mask:0xf bound_ctrl:1
	v_fmac_f32_dpp v238, v12, v218 row_shl:1 row_mask:0xf bank_mask:0xf bound_ctrl:1
	v_fmac_f32_dpp v239, v13, v219 row_shl:1 row_mask:0xf bank_mask:0xf bound_ctrl:1
	v_exp_f32_e64 v240, -v232
	v_pk_fma_f32 v[224:225], v[208:209], v[28:29], v[212:213]
	v_pk_fma_f32 v[226:227], v[206:207], v[28:29], v[212:213]
	v_exp_f32_e64 v241, -v233
	v_pk_fma_f32 v[228:229], v[206:207], v[24:25], v[212:213]
	v_pk_fma_f32 v[230:231], v[206:207], v[20:21], v[212:213]
	v_exp_f32_e64 v242, -v234
	v_pk_fma_f32 v[224:225], v[210:211], v[24:25], v[224:225]
	v_pk_fma_f32 v[226:227], v[208:209], v[24:25], v[226:227]
	v_exp_f32_e64 v243, -v235
	v_pk_fma_f32 v[228:229], v[208:209], v[20:21], v[228:229]
	v_pk_fma_f32 v[230:231], v[208:209], v[16:17], v[230:231]
	v_exp_f32_e64 v244, -v236
	v_pk_fma_f32 v[226:227], v[210:211], v[20:21], v[226:227]
	v_pk_fma_f32 v[228:229], v[210:211], v[16:17], v[228:229]
	v_exp_f32_e64 v245, -v237
	v_fmac_f32_dpp v224, v16, v206 row_shr:1 row_mask:0xf bank_mask:0xf bound_ctrl:1
	v_fmac_f32_dpp v225, v17, v207 row_shr:1 row_mask:0xf bank_mask:0xf bound_ctrl:1
	v_exp_f32_e64 v246, -v238
;     __device__ __forceinline__ void operator()(const f32x4 (&acc)[2][2][4][2], const Unit& u, int wr, int wc, int fr, int fq) const {
;     ...
;                     const f32x4 c0a = ct[cidx], c0b = ct[cidx + 1], c1a = ct[cidx + 2], c1b = ct[cidx + 3];
;                     const f32x2 wv0 = {c0a[0], c1a[0]}, wv1 = {c0a[1], c1a[1]}, wv2 = {c0a[2], c1a[2]}, bv = {c0a[3], c1a[3]};
;                     const f32x2 wg0 = {c0b[0], c1b[0]}, wg1 = {c0b[1], c1b[1]}, wg2 = {c0b[2], c1b[2]}, bg = {c0b[3], c1b[3]};
;                     f32x2 uv[4], ug[4], cv[4];
; #pragma unroll
;                     for (int m = 0; m < 4; ++m) { uv[m] = (f32x2){acc[ai][0][m][n][2 * jp], acc[ai][0][m][n][2 * jp + 1]}; ug[m] = (f32x2){acc[ai][1][m][n][2 * jp], acc[ai][1][m][n][2 * jp + 1]}; }
;                     asm volatile("" : "+v"(uv[0]), "+v"(uv[1]), "+v"(uv[2]), "+v"(uv[3]), "+v"(ug[0]), "+v"(ug[1]), "+v"(ug[2]), "+v"(ug[3]));
;                     {
;                         f32x2 rv[4], lv[4];
; #pragma unroll
;                         for (int m = 0; m < 4; ++m) { uv[m] = uv[m] * rs[m]; rv[m] = (f32x2){dpp_ror1(uv[m][0]), dpp_ror1(uv[m][1])}; lv[m] = (f32x2){dpp_ror15(uv[m][0]), dpp_ror15(uv[m][1])}; }
; #pragma unroll
;                         for (int m = 0; m < 4; ++m) { const f32x2 pv_ = (m > 0 && f0) ? rv[m > 0 ? m - 1 : 0] : rv[m], nv_ = (m < 3 && f15) ? lv[m < 3 ? m + 1 : 3] : lv[m];
;                             cv[m] = bv + wv0 * pv_ + wv1 * uv[m] + wv2 * nv_; }
;                     }
;                     asm volatile("" : "+v"(cv[0]), "+v"(cv[1]), "+v"(cv[2]), "+v"(cv[3]));
;                     {
;                         f32x2 rg[4], lg[4];
; #pragma unroll
;                         for (int m = 0; m < 4; ++m) { ug[m] = ug[m] * rs[m]; rg[m] = (f32x2){dpp_ror1(ug[m][0]), dpp_ror1(ug[m][1])}; lg[m] = (f32x2){dpp_ror15(ug[m][0]), dpp_ror15(ug[m][1])}; }
; #pragma unroll
;                         for (int m = 0; m < 4; ++m) { const f32x2 pg_ = (m > 0 && f0) ? rg[m > 0 ? m - 1 : 0] : rg[m], ng_ = (m < 3 && f15) ? lg[m < 3 ? m + 1 : 3] : lg[m];
;                             const f32x2 cgt = bg + wg0 * pg_ + wg1 * ug[m] + wg2 * ng_;
;                             const f32x2 e = cgt * (-LOG2E);
;                             const f32x2 d = (f32x2){__builtin_amdgcn_exp2f(e[0]), __builtin_amdgcn_exp2f(e[1])} + 1.f;
	v_fmac_f32_dpp v230, v28, v210 row_shl:1 row_mask:0xf bank_mask:0xf bound_ctrl:1
	v_fmac_f32_dpp v231, v29, v211 row_shl:1 row_mask:0xf bank_mask:0xf bound_ctrl:1
	v_exp_f32_e64 v247, -v239
	v_pk_add_f32 v[240:241], v[240:241], 1.0 op_sel_hi:[1,0]
	v_pk_add_f32 v[242:243], v[242:243], 1.0 op_sel_hi:[1,0]
	v_pk_add_f32 v[244:245], v[244:245], 1.0 op_sel_hi:[1,0]
	v_pk_add_f32 v[246:247], v[246:247], 1.0 op_sel_hi:[1,0]
	v_rcp_f32_e32 v240, v240
	v_pk_mul_f32 v[224:225], v[224:225], v[232:233]
	v_pk_mul_f32 v[226:227], v[226:227], v[234:235]
	v_rcp_f32_e32 v241, v241
	v_pk_mul_f32 v[228:229], v[228:229], v[236:237]
	v_pk_mul_f32 v[230:231], v[230:231], v[238:239]
	v_rcp_f32_e32 v242, v242
	v_pk_mul_f32 v[30:31], v[30:31], v[178:179] op_sel_hi:[1,0]
	v_pk_mul_f32 v[26:27], v[26:27], v[180:181] op_sel_hi:[1,0]
	v_rcp_f32_e32 v243, v243
	v_pk_mul_f32 v[22:23], v[22:23], v[182:183] op_sel_hi:[1,0]
	v_pk_mul_f32 v[18:19], v[18:19], v[144:145] op_sel_hi:[1,0]
	v_rcp_f32_e32 v244, v244
	v_pk_mul_f32 v[14:15], v[14:15], v[178:179] op_sel_hi:[1,0]
	v_pk_mul_f32 v[10:11], v[10:11], v[180:181] op_sel_hi:[1,0]
	v_rcp_f32_e32 v245, v245
	v_pk_mul_f32 v[6:7], v[6:7], v[182:183] op_sel_hi:[1,0]
	v_rcp_f32_e32 v246, v246
	v_pk_mul_f32 v[2:3], v[2:3], v[144:145] op_sel_hi:[1,0]
	v_rcp_f32_e32 v247, v247
	s_nop 0
	v_pk_mul_f32 v[224:225], v[224:225], v[240:241]
	v_pk_mul_f32 v[226:227], v[226:227], v[242:243]
	v_pk_mul_f32 v[228:229], v[228:229], v[244:245]
	v_pk_mul_f32 v[230:231], v[230:231], v[246:247]
	v_cvt_pk_bf16_f32 v130, v224, v225
	v_cvt_pk_bf16_f32 v134, v226, v227
	v_cvt_pk_bf16_f32 v138, v228, v229
	v_cvt_pk_bf16_f32 v142, v230, v231
	s_waitcnt vmcnt(0)
	v_pk_fma_f32 v[232:233], v[200:201], v[14:15], v[204:205]
	v_pk_fma_f32 v[234:235], v[198:199], v[14:15], v[204:205]
	v_pk_fma_f32 v[236:237], v[198:199], v[10:11], v[204:205]
	v_pk_fma_f32 v[238:239], v[198:199], v[6:7], v[204:205]
	v_pk_fma_f32 v[232:233], v[202:203], v[10:11], v[232:233]
	v_pk_fma_f32 v[234:235], v[200:201], v[10:11], v[234:235]
	v_pk_fma_f32 v[236:237], v[200:201], v[6:7], v[236:237]
	v_pk_fma_f32 v[238:239], v[200:201], v[2:3], v[238:239]
	v_pk_fma_f32 v[234:235], v[202:203], v[6:7], v[234:235]
	v_pk_fma_f32 v[236:237], v[202:203], v[2:3], v[236:237]
	v_fmac_f32_dpp v232, v2, v198 row_shr:1 row_mask:0xf bank_mask:0xf bound_ctrl:1
	v_fmac_f32_dpp v233, v3, v199 row_shr:1 row_mask:0xf bank_mask:0xf bound_ctrl:1
	v_fmac_f32_dpp v238, v14, v202 row_shl:1 row_mask:0xf bank_mask:0xf bound_ctrl:1
	v_fmac_f32_dpp v239, v15, v203 row_shl:1 row_mask:0xf bank_mask:0xf bound_ctrl:1
	v_exp_f32_e64 v240, -v232
	v_pk_fma_f32 v[224:225], v[192:193], v[30:31], v[196:197]
	v_pk_fma_f32 v[226:227], v[190:191], v[30:31], v[196:197]
	v_exp_f32_e64 v241, -v233
	v_pk_fma_f32 v[228:229], v[190:191], v[26:27], v[196:197]
	v_pk_fma_f32 v[230:231], v[190:191], v[22:23], v[196:197]
	v_exp_f32_e64 v242, -v234
	v_pk_fma_f32 v[224:225], v[194:195], v[26:27], v[224:225]
	v_pk_fma_f32 v[226:227], v[192:193], v[26:27], v[226:227]
	v_exp_f32_e64 v243, -v235
	v_pk_fma_f32 v[228:229], v[192:193], v[22:23], v[228:229]
	v_pk_fma_f32 v[230:231], v[192:193], v[18:19], v[230:231]
	v_exp_f32_e64 v244, -v236
	v_pk_fma_f32 v[226:227], v[194:195], v[22:23], v[226:227]
	v_pk_fma_f32 v[228:229], v[194:195], v[18:19], v[228:229]
	v_exp_f32_e64 v245, -v237
	v_fmac_f32_dpp v224, v18, v190 row_shr:1 row_mask:0xf bank_mask:0xf bound_ctrl:1
	v_fmac_f32_dpp v225, v19, v191 row_shr:1 row_mask:0xf bank_mask:0xf bound_ctrl:1
	v_exp_f32_e64 v246, -v238
	v_fmac_f32_dpp v230, v30, v194 row_shl:1 row_mask:0xf bank_mask:0xf bound_ctrl:1
	v_fmac_f32_dpp v231, v31, v195 row_shl:1 row_mask:0xf bank_mask:0xf bound_ctrl:1
	v_exp_f32_e64 v247, -v239
	v_pk_add_f32 v[240:241], v[240:241], 1.0 op_sel_hi:[1,0]
	v_pk_add_f32 v[242:243], v[242:243], 1.0 op_sel_hi:[1,0]
	v_pk_add_f32 v[244:245], v[244:245], 1.0 op_sel_hi:[1,0]
	v_pk_add_f32 v[246:247], v[246:247], 1.0 op_sel_hi:[1,0]
	v_rcp_f32_e32 v240, v240
	v_pk_mul_f32 v[224:225], v[224:225], v[232:233]
	v_rcp_f32_e32 v241, v241
	v_pk_mul_f32 v[226:227], v[226:227], v[234:235]
	v_rcp_f32_e32 v242, v242
	v_pk_mul_f32 v[228:229], v[228:229], v[236:237]
	v_rcp_f32_e32 v243, v243
	v_pk_mul_f32 v[230:231], v[230:231], v[238:239]
	v_rcp_f32_e32 v244, v244
	v_rcp_f32_e32 v245, v245
	v_rcp_f32_e32 v246, v246
	v_rcp_f32_e32 v247, v247
	s_nop 0
	v_pk_mul_f32 v[224:225], v[224:225], v[240:241]
	v_pk_mul_f32 v[226:227], v[226:227], v[242:243]
	v_pk_mul_f32 v[228:229], v[228:229], v[244:245]
	v_pk_mul_f32 v[230:231], v[230:231], v[246:247]
	v_cvt_pk_bf16_f32 v131, v224, v225
	v_cvt_pk_bf16_f32 v135, v226, v227
	v_cvt_pk_bf16_f32 v139, v228, v229
	v_cvt_pk_bf16_f32 v143, v230, v231
	s_sub_i32 s51, s91, s89
	s_sub_i32 s66, s51, 4
	s_max_i32 s66, s66, 0
	v_add_u32_e32 v176, -4, v164
	v_cmp_gt_u32_e32 vcc, s66, v176
	v_add_u32_e32 v176, 0, v174
	v_add_u32_e32 v176, s88, v176
	v_mad_u32_u24 v248, v176, s54, v165
	s_mov_b64 exec, vcc
	global_store_dwordx4 v248, v[128:131], s[86:87]
	s_mov_b64 exec, -1
	s_sub_i32 s66, s51, 1
	s_max_i32 s66, s66, 0
	v_cmp_gt_u32_e32 vcc, s66, v164
	v_add_u32_e32 v176, 1, v174
	v_add_u32_e32 v176, s88, v176
	v_mad_u32_u24 v249, v176, s54, v165
	s_mov_b64 exec, vcc
	global_store_dwordx4 v249, v[132:135], s[86:87]
	s_mov_b64 exec, -1
	s_sub_i32 s66, s51, 2
	s_max_i32 s66, s66, 0
	v_cmp_gt_u32_e32 vcc, s66, v164
	v_add_u32_e32 v176, 2, v174
	v_add_u32_e32 v176, s88, v176
	v_mad_u32_u24 v250, v176, s54, v165
	s_mov_b64 exec, vcc
	global_store_dwordx4 v250, v[136:139], s[86:87]
	s_mov_b64 exec, -1
	s_sub_i32 s66, s51, 3
	s_min_i32 s66, s66, 60
	s_max_i32 s66, s66, 0
	v_cmp_gt_u32_e32 vcc, s66, v164
	v_add_u32_e32 v176, 3, v174
	v_add_u32_e32 v176, s88, v176
	v_mad_u32_u24 v251, v176, s54, v165
	s_mov_b64 exec, vcc
	global_store_dwordx4 v251, v[140:143], s[86:87]
	s_mov_b64 exec, -1
	s_mov_b64 s[2:3], exec
